# same as previous plus two wait states restored where deleting s_setprio had shortened an MFMA-result to VALU-write distance
# baseline (speedup 1.0000x reference)
;     __host__ __device__ bool next(int i, Unit& u) const { const long L = (long)i * G + c; if (L >= maxL) return false; return unit_of(L, u); }
;     __device__ __forceinline__ const char* a_base(const Gemm& g, const Unit& u, size_t tstep) const { return (const char*)g.A + (size_t)u.pm * tstep; }
;     __device__ __forceinline__ const char* b_base(const Gemm& g, const Unit& u, size_t tstep) const { return (const char*)g.Bt + (size_t)u.pn * tstep; }
; #define PG8_STAGE(bufoff, gbase, voff) do { _Pragma("unroll") for (int _i = 0; _i < 2; ++_i) \
;         __builtin_amdgcn_global_load_lds((const unsigned*)((const char*)(gbase) + (voff)[_i]), (PG8_LAS unsigned*)(lds + (bufoff) + ldsw + _i * 8192), 16, 0, 0); } while (0)
; #define PG8_WAIT_V(n) asm volatile("s_waitcnt vmcnt(" #n ")" ::: "memory")
; #define PG8_WAIT_L(n) asm volatile("s_waitcnt lgkmcnt(" #n ")" ::: "memory")
; template <class Epi, class Sched, bool ALIGN_EPI = false, bool SP2 = false>
; __device__ __forceinline__ void gemm_phase(PG8_LAS unsigned char* lds, const Gemm g, const Sched& S, const Epi& E, const int wave_id_in) {
;     ...
;         const bool has_next = S.next(ui + 1, nxt);
;         const char* nA = has_next ? S.a_base(g, nxt, tstep) : cA; const char* nB = has_next ? S.b_base(g, nxt, tstep) : cB;
;         for (int t = 0; t < nt; t += 2) {
;             const bool last = (t == nt - 2);
;             const char* a1 = cA + (size_t)(t + 1) * kstep;
;             const char* a2 = last ? nA : cA + (size_t)(t + 2) * kstep; const char* b2 = last ? nB : cB + (size_t)(t + 2) * kstep;
;             const char* a3 = a2 + kstep; const char* b3 = b2 + kstep;
;             if (last && has_next) S.a_ready(nxt);
;             if constexpr (SP2) {
;             PG8_LDB(B0, 0, 0); PG8_LDB(B1, 0, 1); PG8_SCHED; PG8_LDA(At, 0, 0); PG8_STAGE(PG8_SA(1, 1), a1 + hstep, voffA);
;             PG8_WAIT_V(8); PG8_WAIT_L(0); PG8_BAR; __builtin_amdgcn_s_setprio(1); PG8_MMA(0, 0, At, B0); PG8_MMA(0, 1, At, B1); __builtin_amdgcn_s_setprio(0); PG8_BAR; PG8_SCHED;
;             PG8_LDA(At, 0, 1); PG8_STAGE(PG8_SB(0, 0), b2, voffB); PG8_STAGE(PG8_SB(0, 1), b2 + hstep, voffB); PG8_STAGE(PG8_SA(0, 0), a2, voffA);
;             PG8_WAIT_V(8); PG8_WAIT_L(0); PG8_BAR; __builtin_amdgcn_s_setprio(1); PG8_MMA(1, 0, At, B0); PG8_MMA(1, 1, At, B1); __builtin_amdgcn_s_setprio(0); PG8_BAR; PG8_SCHED;
.LBB0_818:
	s_ashr_i32 s67, s66, 31
	s_lshl_b64 s[68:69], s[66:67], 20
	s_add_u32 s68, s78, s68
	s_addc_u32 s69, s79, s69
	s_and_b64 s[70:71], s[6:7], exec
	s_cselect_b32 s9, s69, s11
	s_cselect_b32 s27, s68, s10
	s_ashr_i32 s65, s64, 31
	s_lshl_b64 s[70:71], s[64:65], 20
	s_add_u32 s70, s44, s70
	s_addc_u32 s71, s45, s71
	s_and_b64 s[72:73], s[6:7], exec
	s_cselect_b32 s65, s71, s13
	s_cselect_b32 s74, s70, s12
	s_add_u32 s10, s10, 0x80080
	s_addc_u32 s11, s11, 0
	s_add_u32 s75, s12, 0x100
	s_addc_u32 vcc_lo, s13, 0
	s_mov_b32 vcc_hi, -2
	s_waitcnt lgkmcnt(0)
	ds_read_b128 v[44:47], v221
	ds_read_b128 v[48:51], v221 offset:1024
	ds_read_b128 v[56:59], v221 offset:2048
	s_waitcnt lgkmcnt(0)
	ds_read_b128 v[60:63], v221 offset:3072
	ds_read_b128 v[68:71], v222
	ds_read_b128 v[72:75], v222 offset:1024
	ds_read_b128 v[76:79], v222 offset:2048
	ds_read_b128 v[84:87], v222 offset:3072
	s_add_u32 s12, s10, 0xfff80080
	s_addc_u32 s13, s11, -1
	s_cmp_eq_u32 vcc_hi, 28
	s_cselect_b32 s73, s9, s13
	s_cselect_b32 s72, s27, s12
	s_cselect_b32 s13, s65, vcc_lo
	s_cselect_b32 s12, s74, s75
	v_lshl_add_u64 v[208:209], s[10:11], 0, v[194:195]
	s_add_i32 m0, s81, 0xc000
	ds_read_b128 v[92:95], v223
	ds_read_b128 v[96:99], v223 offset:1024
	ds_read_b128 v[120:123], v223 offset:2048
	ds_read_b128 v[124:127], v223 offset:3072
	ds_read_b128 v[168:171], v223 offset:4096
	ds_read_b128 v[180:183], v223 offset:5120
	ds_read_b128 v[200:203], v223 offset:6144
	ds_read_b128 v[204:207], v223 offset:7168
	global_load_lds_dwordx4 v[208:209], off
	v_lshl_add_u64 v[208:209], s[10:11], 0, v[196:197]
	s_add_i32 m0, s81, 0xe000
	s_nop 0
	global_load_lds_dwordx4 v[208:209], off
	s_waitcnt vmcnt(8)
	s_waitcnt lgkmcnt(0)
	s_barrier
	v_mfma_f32_16x16x32_bf16 v[40:43], v[44:47], v[92:95], 0
	v_mfma_f32_16x16x32_bf16 v[36:39], v[56:59], v[92:95], 0
	v_mfma_f32_16x16x32_bf16 v[104:107], v[68:71], v[92:95], 0
	v_mfma_f32_16x16x32_bf16 v[92:95], v[76:79], v[92:95], 0
	v_mfma_f32_16x16x32_bf16 v[108:111], v[76:79], v[120:123], 0
	v_mfma_f32_16x16x32_bf16 v[40:43], v[48:51], v[96:99], v[40:43]
	v_mfma_f32_16x16x32_bf16 v[36:39], v[60:63], v[96:99], v[36:39]
	v_mfma_f32_16x16x32_bf16 v[172:175], v[44:47], v[120:123], 0
	v_mfma_f32_16x16x32_bf16 v[164:167], v[56:59], v[120:123], 0
	v_mfma_f32_16x16x32_bf16 v[104:107], v[72:75], v[96:99], v[104:107]
	v_mfma_f32_16x16x32_bf16 v[92:95], v[84:87], v[96:99], v[92:95]
	v_mfma_f32_16x16x32_bf16 v[96:99], v[68:71], v[120:123], 0
	v_mfma_f32_16x16x32_bf16 v[120:123], v[84:87], v[124:127], v[108:111]
	v_mfma_f32_16x16x32_bf16 v[108:111], v[68:71], v[168:171], 0
	v_mfma_f32_16x16x32_bf16 v[172:175], v[48:51], v[124:127], v[172:175]
	v_mfma_f32_16x16x32_bf16 v[164:167], v[60:63], v[124:127], v[164:167]
	v_mfma_f32_16x16x32_bf16 v[96:99], v[72:75], v[124:127], v[96:99]
	v_mfma_f32_16x16x32_bf16 v[124:127], v[72:75], v[180:183], v[108:111]
	v_mfma_f32_16x16x32_bf16 v[108:111], v[76:79], v[168:171], 0
	v_mfma_f32_16x16x32_bf16 v[136:139], v[84:87], v[180:183], v[108:111]
	v_mfma_f32_16x16x32_bf16 v[108:111], v[68:71], v[200:203], 0
	v_mfma_f32_16x16x32_bf16 v[156:159], v[44:47], v[168:171], 0
	v_mfma_f32_16x16x32_bf16 v[152:155], v[56:59], v[168:171], 0
	v_mfma_f32_16x16x32_bf16 v[160:163], v[44:47], v[200:203], 0
	v_mfma_f32_16x16x32_bf16 v[132:135], v[56:59], v[200:203], 0
	v_mfma_f32_16x16x32_bf16 v[116:119], v[72:75], v[204:207], v[108:111]
	v_mfma_f32_16x16x32_bf16 v[108:111], v[76:79], v[200:203], 0
	v_mfma_f32_16x16x32_bf16 v[156:159], v[48:51], v[180:183], v[156:159]
	v_mfma_f32_16x16x32_bf16 v[152:155], v[60:63], v[180:183], v[152:155]
	v_mfma_f32_16x16x32_bf16 v[160:163], v[48:51], v[204:207], v[160:163]
	v_mfma_f32_16x16x32_bf16 v[132:135], v[60:63], v[204:207], v[132:135]
	v_mfma_f32_16x16x32_bf16 v[112:115], v[84:87], v[204:207], v[108:111]
	s_barrier
	s_add_i32 s40, s5, s80
	v_lshl_add_u64 v[216:217], s[12:13], 0, v[186:187]
	s_mov_b32 m0, s40
	ds_read_b128 v[108:111], v223 offset:16384
	ds_read_b128 v[140:143], v223 offset:17408
	ds_read_b128 v[144:147], v223 offset:18432
	ds_read_b128 v[148:151], v223 offset:19456
	ds_read_b128 v[168:171], v223 offset:20480
	ds_read_b128 v[180:183], v223 offset:21504
	ds_read_b128 v[200:203], v223 offset:22528
	ds_read_b128 v[204:207], v223 offset:23552
	global_load_lds_dwordx4 v[216:217], off
	s_add_i32 m0, s40, 0x2000
	s_add_u32 s40, s12, 0x80000
	v_lshl_add_u64 v[218:219], s[12:13], 0, v[190:191]
	s_addc_u32 s41, s13, 0
	s_add_i32 s77, s28, s80
	global_load_lds_dwordx4 v[218:219], off
	v_lshl_add_u64 v[208:209], s[40:41], 0, v[186:187]
	s_mov_b32 m0, s77
	v_lshl_add_u64 v[226:227], s[72:73], 0, v[184:185]
	global_load_lds_dwordx4 v[208:209], off
	v_lshl_add_u64 v[208:209], s[40:41], 0, v[190:191]
	s_add_i32 m0, s77, 0x2000
	v_lshl_add_u64 v[228:229], s[72:73], 0, v[188:189]
	global_load_lds_dwordx4 v[208:209], off
	s_mov_b32 m0, s81
	s_nop 0
	global_load_lds_dwordx4 v[226:227], off
	s_mov_b32 m0, s82
	s_nop 0
	global_load_lds_dwordx4 v[228:229], off
	s_waitcnt vmcnt(8)
	s_waitcnt lgkmcnt(0)
	s_barrier
; #define PG8_STAGE(bufoff, gbase, voff) do { _Pragma("unroll") for (int _i = 0; _i < 2; ++_i) \
;         __builtin_amdgcn_global_load_lds((const unsigned*)((const char*)(gbase) + (voff)[_i]), (PG8_LAS unsigned*)(lds + (bufoff) + ldsw + _i * 8192), 16, 0, 0); } while (0)
; #define PG8_LDA(dst, b, h) do { _Pragma("unroll") for (int m = 0; m < 4; ++m) _Pragma("unroll") for (int k = 0; k < 2; ++k) dst[m][k] = *(const PG8_LAS bf16x8*)(lds + PG8_SA(b, h) + aoff + m * 2048 + k * 1024); } while (0)
; #define PG8_LDB(dst, b, h) do { _Pragma("unroll") for (int n = 0; n < 2; ++n) _Pragma("unroll") for (int k = 0; k < 2; ++k) dst[n][k] = *(const PG8_LAS bf16x8*)(lds + PG8_SB(b, h) + boff + n * 2048 + k * 1024); } while (0)
; #define PG8_MMA(ai, bj, At, Bt) do { _Pragma("unroll") for (int m = 0; m < 4; ++m) _Pragma("unroll") for (int n = 0; n < 2; ++n) _Pragma("unroll") for (int k = 0; k < 2; ++k) \
;         acc[ai][bj][m][n] = __builtin_amdgcn_mfma_f32_16x16x32_bf16(Bt[n][k], At[m][k], acc[ai][bj][m][n], 0, 0, 0); } while (0)
; #define PG8_WAIT_V(n) asm volatile("s_waitcnt vmcnt(" #n ")" ::: "memory")
; #define PG8_WAIT_L(n) asm volatile("s_waitcnt lgkmcnt(" #n ")" ::: "memory")
; #define PG8_BAR __builtin_amdgcn_s_barrier()
; #define PG8_SCHED __builtin_amdgcn_sched_barrier(0)
; template <class Epi, class Sched, bool ALIGN_EPI = false, bool SP2 = false>
; __device__ __forceinline__ void gemm_phase(PG8_LAS unsigned char* lds, const Gemm g, const Sched& S, const Epi& E, const int wave_id_in) {
;     ...
;             PG8_WAIT_V(8); PG8_WAIT_L(0); PG8_BAR; __builtin_amdgcn_s_setprio(1); PG8_MMA(1, 0, At, B0); PG8_MMA(1, 1, At, B1); __builtin_amdgcn_s_setprio(0); PG8_BAR; PG8_SCHED;
;             PG8_LDB(B0, 1, 0); PG8_LDB(B1, 1, 1); PG8_SCHED; PG8_LDA(At, 1, 0); PG8_STAGE(PG8_SA(0, 1), a2 + hstep, voffA);
;             PG8_WAIT_V(8); PG8_WAIT_L(0); PG8_BAR; __builtin_amdgcn_s_setprio(1); PG8_MMA(0, 0, At, B0); PG8_MMA(0, 1, At, B1); __builtin_amdgcn_s_setprio(0); PG8_BAR; PG8_SCHED;
	v_mfma_f32_16x16x32_bf16 v[128:131], v[44:47], v[108:111], 0
	v_mfma_f32_16x16x32_bf16 v[64:67], v[56:59], v[108:111], 0
	v_mfma_f32_16x16x32_bf16 v[100:103], v[44:47], v[144:147], 0
	v_mfma_f32_16x16x32_bf16 v[88:91], v[56:59], v[144:147], 0
	v_mfma_f32_16x16x32_bf16 v[28:31], v[44:47], v[168:171], 0
	v_mfma_f32_16x16x32_bf16 v[24:27], v[56:59], v[168:171], 0
	v_mfma_f32_16x16x32_bf16 v[44:47], v[44:47], v[200:203], 0
	v_mfma_f32_16x16x32_bf16 v[32:35], v[76:79], v[108:111], 0
	v_mfma_f32_16x16x32_bf16 v[20:23], v[68:71], v[144:147], 0
	v_mfma_f32_16x16x32_bf16 v[16:19], v[76:79], v[144:147], 0
	v_mfma_f32_16x16x32_bf16 v[12:15], v[68:71], v[168:171], 0
	v_mfma_f32_16x16x32_bf16 v[8:11], v[76:79], v[168:171], 0
	v_mfma_f32_16x16x32_bf16 v[4:7], v[68:71], v[200:203], 0
	v_mfma_f32_16x16x32_bf16 v[0:3], v[76:79], v[200:203], 0
	v_mfma_f32_16x16x32_bf16 v[128:131], v[48:51], v[140:143], v[128:131]
	v_mfma_f32_16x16x32_bf16 v[64:67], v[60:63], v[140:143], v[64:67]
	v_mfma_f32_16x16x32_bf16 v[100:103], v[48:51], v[148:151], v[100:103]
	v_mfma_f32_16x16x32_bf16 v[88:91], v[60:63], v[148:151], v[88:91]
	v_mfma_f32_16x16x32_bf16 v[28:31], v[48:51], v[180:183], v[28:31]
	v_mfma_f32_16x16x32_bf16 v[24:27], v[60:63], v[180:183], v[24:27]
	v_mfma_f32_16x16x32_bf16 v[44:47], v[48:51], v[204:207], v[44:47]
	v_mfma_f32_16x16x32_bf16 v[48:51], v[56:59], v[200:203], 0
	v_mfma_f32_16x16x32_bf16 v[52:55], v[68:71], v[108:111], 0
	v_mfma_f32_16x16x32_bf16 v[32:35], v[84:87], v[140:143], v[32:35]
	v_mfma_f32_16x16x32_bf16 v[20:23], v[72:75], v[148:151], v[20:23]
	v_mfma_f32_16x16x32_bf16 v[16:19], v[84:87], v[148:151], v[16:19]
	v_mfma_f32_16x16x32_bf16 v[12:15], v[72:75], v[180:183], v[12:15]
	v_mfma_f32_16x16x32_bf16 v[8:11], v[84:87], v[180:183], v[8:11]
	v_mfma_f32_16x16x32_bf16 v[4:7], v[72:75], v[204:207], v[4:7]
	v_mfma_f32_16x16x32_bf16 v[0:3], v[84:87], v[204:207], v[0:3]
	v_mfma_f32_16x16x32_bf16 v[48:51], v[60:63], v[204:207], v[48:51]
	v_mfma_f32_16x16x32_bf16 v[56:59], v[72:75], v[140:143], v[52:55]
	s_barrier
	s_add_i32 s77, 0, 0x18000
	s_add_i32 s76, 0, 0x1c000
	v_add_u32_e32 v72, s77, v220
	v_add_u32_e32 v80, s76, v220
	ds_read_b128 v[52:55], v72
	ds_read_b128 v[60:63], v72 offset:1024
	ds_read_b128 v[68:71], v72 offset:2048
	ds_read_b128 v[72:75], v72 offset:3072
	ds_read_b128 v[76:79], v80
	ds_read_b128 v[84:87], v80 offset:1024
	ds_read_b128 v[168:171], v80 offset:2048
	ds_read_b128 v[180:183], v80 offset:3072
	s_add_u32 s40, s72, 0x80000
	s_addc_u32 s41, s73, 0
	s_mov_b32 m0, s83
	v_lshl_add_u64 v[148:149], s[40:41], 0, v[184:185]
	ds_read_b128 v[80:83], v223 offset:32768
	ds_read_b128 v[108:111], v223 offset:33792
	ds_read_b128 v[140:143], v223 offset:34816
	ds_read_b128 v[144:147], v223 offset:35840
	ds_read_b128 v[176:179], v223 offset:36864
	ds_read_b128 v[200:203], v223 offset:37888
	ds_read_b128 v[204:207], v223 offset:38912
	ds_read_b128 v[208:211], v223 offset:39936
	global_load_lds_dwordx4 v[148:149], off
	v_lshl_add_u64 v[148:149], s[40:41], 0, v[188:189]
	s_mov_b32 m0, s84
	s_nop 0
	global_load_lds_dwordx4 v[148:149], off
	s_waitcnt vmcnt(8)
	s_waitcnt lgkmcnt(0)
	s_barrier
	v_mfma_f32_16x16x32_bf16 v[148:151], v[52:55], v[140:143], v[172:175]
	v_mfma_f32_16x16x32_bf16 v[172:175], v[60:63], v[144:147], v[148:151]
	v_mfma_f32_16x16x32_bf16 v[148:151], v[68:71], v[140:143], v[164:167]
	v_mfma_f32_16x16x32_bf16 v[164:167], v[72:75], v[144:147], v[148:151]
	v_mfma_f32_16x16x32_bf16 v[148:151], v[52:55], v[176:179], v[156:159]
	v_mfma_f32_16x16x32_bf16 v[40:43], v[52:55], v[80:83], v[40:43]
	v_mfma_f32_16x16x32_bf16 v[36:39], v[68:71], v[80:83], v[36:39]
	v_mfma_f32_16x16x32_bf16 v[156:159], v[60:63], v[200:203], v[148:151]
	v_mfma_f32_16x16x32_bf16 v[148:151], v[68:71], v[176:179], v[152:155]
	v_mfma_f32_16x16x32_bf16 v[104:107], v[76:79], v[80:83], v[104:107]
	v_mfma_f32_16x16x32_bf16 v[80:83], v[168:171], v[80:83], v[92:95]
	v_mfma_f32_16x16x32_bf16 v[40:43], v[60:63], v[108:111], v[40:43]
	v_mfma_f32_16x16x32_bf16 v[36:39], v[72:75], v[108:111], v[36:39]
	v_mfma_f32_16x16x32_bf16 v[152:155], v[72:75], v[200:203], v[148:151]
	v_mfma_f32_16x16x32_bf16 v[148:151], v[52:55], v[204:207], v[160:163]
	v_mfma_f32_16x16x32_bf16 v[104:107], v[84:87], v[108:111], v[104:107]
	v_mfma_f32_16x16x32_bf16 v[108:111], v[180:183], v[108:111], v[80:83]
	v_mfma_f32_16x16x32_bf16 v[80:83], v[76:79], v[140:143], v[96:99]
	v_mfma_f32_16x16x32_bf16 v[160:163], v[60:63], v[208:211], v[148:151]
	v_mfma_f32_16x16x32_bf16 v[148:151], v[84:87], v[144:147], v[80:83]
	v_mfma_f32_16x16x32_bf16 v[80:83], v[168:171], v[140:143], v[120:123]
	v_mfma_f32_16x16x32_bf16 v[144:147], v[180:183], v[144:147], v[80:83]
	v_mfma_f32_16x16x32_bf16 v[80:83], v[76:79], v[176:179], v[124:127]
	v_mfma_f32_16x16x32_bf16 v[140:143], v[84:87], v[200:203], v[80:83]
	v_mfma_f32_16x16x32_bf16 v[80:83], v[168:171], v[176:179], v[136:139]
	v_mfma_f32_16x16x32_bf16 v[136:139], v[180:183], v[200:203], v[80:83]
	v_mfma_f32_16x16x32_bf16 v[80:83], v[76:79], v[204:207], v[116:119]
	v_mfma_f32_16x16x32_bf16 v[132:135], v[68:71], v[204:207], v[132:135]
	v_mfma_f32_16x16x32_bf16 v[116:119], v[84:87], v[208:211], v[80:83]
	v_mfma_f32_16x16x32_bf16 v[80:83], v[168:171], v[204:207], v[112:115]
	v_mfma_f32_16x16x32_bf16 v[132:135], v[72:75], v[208:211], v[132:135]
	v_mfma_f32_16x16x32_bf16 v[112:115], v[180:183], v[208:211], v[80:83]
	s_barrier
; #define PG8_STAGE(bufoff, gbase, voff) do { _Pragma("unroll") for (int _i = 0; _i < 2; ++_i) \
;         __builtin_amdgcn_global_load_lds((const unsigned*)((const char*)(gbase) + (voff)[_i]), (PG8_LAS unsigned*)(lds + (bufoff) + ldsw + _i * 8192), 16, 0, 0); } while (0)
; #define PG8_LDA(dst, b, h) do { _Pragma("unroll") for (int m = 0; m < 4; ++m) _Pragma("unroll") for (int k = 0; k < 2; ++k) dst[m][k] = *(const PG8_LAS bf16x8*)(lds + PG8_SA(b, h) + aoff + m * 2048 + k * 1024); } while (0)
; #define PG8_LDB(dst, b, h) do { _Pragma("unroll") for (int n = 0; n < 2; ++n) _Pragma("unroll") for (int k = 0; k < 2; ++k) dst[n][k] = *(const PG8_LAS bf16x8*)(lds + PG8_SB(b, h) + boff + n * 2048 + k * 1024); } while (0)
; #define PG8_MMA(ai, bj, At, Bt) do { _Pragma("unroll") for (int m = 0; m < 4; ++m) _Pragma("unroll") for (int n = 0; n < 2; ++n) _Pragma("unroll") for (int k = 0; k < 2; ++k) \
;         acc[ai][bj][m][n] = __builtin_amdgcn_mfma_f32_16x16x32_bf16(Bt[n][k], At[m][k], acc[ai][bj][m][n], 0, 0, 0); } while (0)
; #define PG8_WAIT_V(n) asm volatile("s_waitcnt vmcnt(" #n ")" ::: "memory")
; #define PG8_WAIT_L(n) asm volatile("s_waitcnt lgkmcnt(" #n ")" ::: "memory")
; #define PG8_BAR __builtin_amdgcn_s_barrier()
; #define PG8_SCHED __builtin_amdgcn_sched_barrier(0)
; template <class Epi, class Sched, bool ALIGN_EPI = false, bool SP2 = false>
; __device__ __forceinline__ void gemm_phase(PG8_LAS unsigned char* lds, const Gemm g, const Sched& S, const Epi& E, const int wave_id_in) {
;     ...
;             PG8_LDB(B0, 0, 0); PG8_LDB(B1, 0, 1); PG8_SCHED; PG8_LDA(At, 0, 0); PG8_STAGE(PG8_SA(1, 1), a1 + hstep, voffA);
;             PG8_WAIT_V(8); PG8_WAIT_L(0); PG8_BAR; __builtin_amdgcn_s_setprio(1); PG8_MMA(0, 0, At, B0); PG8_MMA(0, 1, At, B1); __builtin_amdgcn_s_setprio(0); PG8_BAR; PG8_SCHED;
;             PG8_LDA(At, 0, 1); PG8_STAGE(PG8_SB(0, 0), b2, voffB); PG8_STAGE(PG8_SB(0, 1), b2 + hstep, voffB); PG8_STAGE(PG8_SA(0, 0), a2, voffA);
;     ...
;             PG8_LDA(At, 1, 1); PG8_STAGE(PG8_SB(1, 0), b3, voffB); PG8_STAGE(PG8_SB(1, 1), b3 + hstep, voffB); PG8_STAGE(PG8_SA(1, 0), a3, voffA);
;             PG8_WAIT_V(8); PG8_WAIT_L(0); PG8_BAR; __builtin_amdgcn_s_setprio(1); PG8_MMA(1, 0, At, B0); PG8_MMA(1, 1, At, B1); __builtin_amdgcn_s_setprio(0); PG8_BAR; PG8_SCHED;
	s_add_i32 s40, s77, s80
	s_nop 2
	s_nop 0
	v_lshl_add_u64 v[80:81], v[216:217], 0, s[34:35]
	s_mov_b32 m0, s40
	ds_read_b128 v[92:95], v223 offset:49152
	ds_read_b128 v[96:99], v223 offset:50176
	ds_read_b128 v[120:123], v223 offset:51200
	ds_read_b128 v[124:127], v223 offset:52224
	ds_read_b128 v[200:203], v223 offset:53248
	ds_read_b128 v[204:207], v223 offset:54272
	ds_read_b128 v[208:211], v223 offset:55296
	ds_read_b128 v[212:215], v223 offset:56320
	global_load_lds_dwordx4 v[80:81], off
	s_add_i32 m0, s40, 0x2000
	s_add_u32 s12, s12, 0x80080
	v_lshl_add_u64 v[80:81], v[218:219], 0, s[34:35]
	s_addc_u32 s13, s13, 0
	s_add_i32 s40, s76, s80
	global_load_lds_dwordx4 v[80:81], off
	v_lshl_add_u64 v[80:81], s[12:13], 0, v[186:187]
	s_mov_b32 m0, s40
	s_nop 0
	global_load_lds_dwordx4 v[80:81], off
	v_lshl_add_u64 v[80:81], s[12:13], 0, v[190:191]
	s_add_i32 m0, s40, 0x2000
	s_nop 0
	global_load_lds_dwordx4 v[80:81], off
	v_lshl_add_u64 v[80:81], v[226:227], 0, s[34:35]
	s_mov_b32 m0, s87
	s_nop 0
	global_load_lds_dwordx4 v[80:81], off
	v_lshl_add_u64 v[80:81], v[228:229], 0, s[34:35]
	s_mov_b32 m0, s88
	s_nop 0
	global_load_lds_dwordx4 v[80:81], off
	s_waitcnt vmcnt(8)
	s_waitcnt lgkmcnt(0)
	s_barrier
	v_mfma_f32_16x16x32_bf16 v[80:83], v[52:55], v[92:95], v[128:131]
	v_mfma_f32_16x16x32_bf16 v[44:47], v[52:55], v[208:211], v[44:47]
	v_mfma_f32_16x16x32_bf16 v[128:131], v[60:63], v[96:99], v[80:83]
	v_mfma_f32_16x16x32_bf16 v[80:83], v[52:55], v[120:123], v[100:103]
	v_mfma_f32_16x16x32_bf16 v[176:179], v[60:63], v[212:215], v[44:47]
	v_mfma_f32_16x16x32_bf16 v[44:47], v[68:71], v[208:211], v[48:51]
	v_mfma_f32_16x16x32_bf16 v[64:67], v[68:71], v[92:95], v[64:67]
	v_mfma_f32_16x16x32_bf16 v[100:103], v[60:63], v[124:127], v[80:83]
	v_mfma_f32_16x16x32_bf16 v[80:83], v[68:71], v[120:123], v[88:91]
	v_mfma_f32_16x16x32_bf16 v[28:31], v[52:55], v[200:203], v[28:31]
	v_mfma_f32_16x16x32_bf16 v[24:27], v[68:71], v[200:203], v[24:27]
	v_mfma_f32_16x16x32_bf16 v[52:55], v[72:75], v[212:215], v[44:47]
	v_mfma_f32_16x16x32_bf16 v[44:47], v[76:79], v[92:95], v[56:59]
	v_mfma_f32_16x16x32_bf16 v[32:35], v[168:171], v[92:95], v[32:35]
	v_mfma_f32_16x16x32_bf16 v[20:23], v[76:79], v[120:123], v[20:23]
	v_mfma_f32_16x16x32_bf16 v[16:19], v[168:171], v[120:123], v[16:19]
	v_mfma_f32_16x16x32_bf16 v[12:15], v[76:79], v[200:203], v[12:15]
	v_mfma_f32_16x16x32_bf16 v[8:11], v[168:171], v[200:203], v[8:11]
	v_mfma_f32_16x16x32_bf16 v[4:7], v[76:79], v[208:211], v[4:7]
	v_mfma_f32_16x16x32_bf16 v[0:3], v[168:171], v[208:211], v[0:3]
	v_mfma_f32_16x16x32_bf16 v[64:67], v[72:75], v[96:99], v[64:67]
	v_mfma_f32_16x16x32_bf16 v[88:91], v[72:75], v[124:127], v[80:83]
	v_mfma_f32_16x16x32_bf16 v[28:31], v[60:63], v[204:207], v[28:31]
	v_mfma_f32_16x16x32_bf16 v[24:27], v[72:75], v[204:207], v[24:27]
	v_mfma_f32_16x16x32_bf16 v[80:83], v[84:87], v[96:99], v[44:47]
	v_mfma_f32_16x16x32_bf16 v[32:35], v[180:183], v[96:99], v[32:35]
	v_mfma_f32_16x16x32_bf16 v[20:23], v[84:87], v[124:127], v[20:23]
	v_mfma_f32_16x16x32_bf16 v[16:19], v[180:183], v[124:127], v[16:19]
	v_mfma_f32_16x16x32_bf16 v[12:15], v[84:87], v[204:207], v[12:15]
	v_mfma_f32_16x16x32_bf16 v[8:11], v[180:183], v[204:207], v[8:11]
	v_mfma_f32_16x16x32_bf16 v[4:7], v[84:87], v[212:215], v[4:7]
	v_mfma_f32_16x16x32_bf16 v[0:3], v[180:183], v[212:215], v[0:3]
	s_barrier
	s_add_i32 vcc_hi, vcc_hi, 2
	s_add_u32 s10, s10, 0x100
	s_addc_u32 s11, s11, 0
	s_add_u32 s75, s75, 0x100
	s_addc_u32 vcc_lo, vcc_lo, 0
	s_cmp_gt_u32 vcc_hi, 29
	s_cbranch_scc0 .LBB0_819
	s_branch .Lpeel_exit_ffnup
.LBB0_819:
	ds_read_b128 v[44:47], v221
	ds_read_b128 v[48:51], v221 offset:1024
	ds_read_b128 v[56:59], v221 offset:2048
	s_waitcnt lgkmcnt(0)
	ds_read_b128 v[60:63], v221 offset:3072
	ds_read_b128 v[68:71], v222
	ds_read_b128 v[72:75], v222 offset:1024
	ds_read_b128 v[76:79], v222 offset:2048
	ds_read_b128 v[84:87], v222 offset:3072
	s_add_u32 s12, s10, 0xfff80080
	s_addc_u32 s13, s11, -1
	s_cmp_eq_u32 vcc_hi, 28
	s_cselect_b32 s73, s9, s13
	s_cselect_b32 s72, s27, s12
	s_cselect_b32 s13, s65, vcc_lo
	s_cselect_b32 s12, s74, s75
	v_lshl_add_u64 v[208:209], s[10:11], 0, v[194:195]
	s_add_i32 m0, s81, 0xc000
	ds_read_b128 v[92:95], v223
	ds_read_b128 v[96:99], v223 offset:1024
	ds_read_b128 v[120:123], v223 offset:2048
	ds_read_b128 v[124:127], v223 offset:3072
	ds_read_b128 v[168:171], v223 offset:4096
	ds_read_b128 v[180:183], v223 offset:5120
	ds_read_b128 v[200:203], v223 offset:6144
	ds_read_b128 v[204:207], v223 offset:7168
	global_load_lds_dwordx4 v[208:209], off
	v_lshl_add_u64 v[208:209], s[10:11], 0, v[196:197]
	s_add_i32 m0, s81, 0xe000
	s_nop 0
	global_load_lds_dwordx4 v[208:209], off
	s_waitcnt vmcnt(8)
	s_waitcnt lgkmcnt(0)
	s_barrier
; #define PG8_STAGE(bufoff, gbase, voff) do { _Pragma("unroll") for (int _i = 0; _i < 2; ++_i) \
;         __builtin_amdgcn_global_load_lds((const unsigned*)((const char*)(gbase) + (voff)[_i]), (PG8_LAS unsigned*)(lds + (bufoff) + ldsw + _i * 8192), 16, 0, 0); } while (0)
; #define PG8_LDA(dst, b, h) do { _Pragma("unroll") for (int m = 0; m < 4; ++m) _Pragma("unroll") for (int k = 0; k < 2; ++k) dst[m][k] = *(const PG8_LAS bf16x8*)(lds + PG8_SA(b, h) + aoff + m * 2048 + k * 1024); } while (0)
; #define PG8_MMA(ai, bj, At, Bt) do { _Pragma("unroll") for (int m = 0; m < 4; ++m) _Pragma("unroll") for (int n = 0; n < 2; ++n) _Pragma("unroll") for (int k = 0; k < 2; ++k) \
;         acc[ai][bj][m][n] = __builtin_amdgcn_mfma_f32_16x16x32_bf16(Bt[n][k], At[m][k], acc[ai][bj][m][n], 0, 0, 0); } while (0)
; #define PG8_WAIT_V(n) asm volatile("s_waitcnt vmcnt(" #n ")" ::: "memory")
; #define PG8_WAIT_L(n) asm volatile("s_waitcnt lgkmcnt(" #n ")" ::: "memory")
; #define PG8_BAR __builtin_amdgcn_s_barrier()
; #define PG8_SCHED __builtin_amdgcn_sched_barrier(0)
; template <class Epi, class Sched, bool ALIGN_EPI = false, bool SP2 = false>
; __device__ __forceinline__ void gemm_phase(PG8_LAS unsigned char* lds, const Gemm g, const Sched& S, const Epi& E, const int wave_id_in) {
;     ...
;             PG8_WAIT_V(8); PG8_WAIT_L(0); PG8_BAR; __builtin_amdgcn_s_setprio(1); PG8_MMA(0, 0, At, B0); PG8_MMA(0, 1, At, B1); __builtin_amdgcn_s_setprio(0); PG8_BAR; PG8_SCHED;
;             PG8_LDA(At, 0, 1); PG8_STAGE(PG8_SB(0, 0), b2, voffB); PG8_STAGE(PG8_SB(0, 1), b2 + hstep, voffB); PG8_STAGE(PG8_SA(0, 0), a2, voffA);
;             PG8_WAIT_V(8); PG8_WAIT_L(0); PG8_BAR; __builtin_amdgcn_s_setprio(1); PG8_MMA(1, 0, At, B0); PG8_MMA(1, 1, At, B1); __builtin_amdgcn_s_setprio(0); PG8_BAR; PG8_SCHED;
	v_mfma_f32_16x16x32_bf16 v[40:43], v[44:47], v[92:95], v[40:43]
	v_mfma_f32_16x16x32_bf16 v[36:39], v[56:59], v[92:95], v[36:39]
	v_mfma_f32_16x16x32_bf16 v[104:107], v[68:71], v[92:95], v[104:107]
	v_mfma_f32_16x16x32_bf16 v[92:95], v[76:79], v[92:95], v[108:111]
	v_mfma_f32_16x16x32_bf16 v[108:111], v[76:79], v[120:123], v[144:147]
	v_mfma_f32_16x16x32_bf16 v[40:43], v[48:51], v[96:99], v[40:43]
	v_mfma_f32_16x16x32_bf16 v[36:39], v[60:63], v[96:99], v[36:39]
	v_mfma_f32_16x16x32_bf16 v[172:175], v[44:47], v[120:123], v[172:175]
	v_mfma_f32_16x16x32_bf16 v[164:167], v[56:59], v[120:123], v[164:167]
	v_mfma_f32_16x16x32_bf16 v[104:107], v[72:75], v[96:99], v[104:107]
	v_mfma_f32_16x16x32_bf16 v[92:95], v[84:87], v[96:99], v[92:95]
	v_mfma_f32_16x16x32_bf16 v[96:99], v[68:71], v[120:123], v[148:151]
	v_mfma_f32_16x16x32_bf16 v[120:123], v[84:87], v[124:127], v[108:111]
	v_mfma_f32_16x16x32_bf16 v[108:111], v[68:71], v[168:171], v[140:143]
	v_mfma_f32_16x16x32_bf16 v[172:175], v[48:51], v[124:127], v[172:175]
	v_mfma_f32_16x16x32_bf16 v[164:167], v[60:63], v[124:127], v[164:167]
	v_mfma_f32_16x16x32_bf16 v[96:99], v[72:75], v[124:127], v[96:99]
	v_mfma_f32_16x16x32_bf16 v[124:127], v[72:75], v[180:183], v[108:111]
	v_mfma_f32_16x16x32_bf16 v[108:111], v[76:79], v[168:171], v[136:139]
	v_mfma_f32_16x16x32_bf16 v[136:139], v[84:87], v[180:183], v[108:111]
	v_mfma_f32_16x16x32_bf16 v[108:111], v[68:71], v[200:203], v[116:119]
	v_mfma_f32_16x16x32_bf16 v[156:159], v[44:47], v[168:171], v[156:159]
	v_mfma_f32_16x16x32_bf16 v[152:155], v[56:59], v[168:171], v[152:155]
	v_mfma_f32_16x16x32_bf16 v[160:163], v[44:47], v[200:203], v[160:163]
	v_mfma_f32_16x16x32_bf16 v[132:135], v[56:59], v[200:203], v[132:135]
	v_mfma_f32_16x16x32_bf16 v[116:119], v[72:75], v[204:207], v[108:111]
	v_mfma_f32_16x16x32_bf16 v[108:111], v[76:79], v[200:203], v[112:115]
	v_mfma_f32_16x16x32_bf16 v[156:159], v[48:51], v[180:183], v[156:159]
	v_mfma_f32_16x16x32_bf16 v[152:155], v[60:63], v[180:183], v[152:155]
	v_mfma_f32_16x16x32_bf16 v[160:163], v[48:51], v[204:207], v[160:163]
	v_mfma_f32_16x16x32_bf16 v[132:135], v[60:63], v[204:207], v[132:135]
	v_mfma_f32_16x16x32_bf16 v[112:115], v[84:87], v[204:207], v[108:111]
	s_barrier
	s_add_i32 s40, s5, s80
	v_lshl_add_u64 v[216:217], s[12:13], 0, v[186:187]
	s_mov_b32 m0, s40
	ds_read_b128 v[108:111], v223 offset:16384
	ds_read_b128 v[140:143], v223 offset:17408
	ds_read_b128 v[144:147], v223 offset:18432
	ds_read_b128 v[148:151], v223 offset:19456
	ds_read_b128 v[168:171], v223 offset:20480
	ds_read_b128 v[180:183], v223 offset:21504
	ds_read_b128 v[200:203], v223 offset:22528
	ds_read_b128 v[204:207], v223 offset:23552
	global_load_lds_dwordx4 v[216:217], off
	s_add_i32 m0, s40, 0x2000
	s_add_u32 s40, s12, 0x80000
	v_lshl_add_u64 v[218:219], s[12:13], 0, v[190:191]
	s_addc_u32 s41, s13, 0
	s_add_i32 s77, s28, s80
	global_load_lds_dwordx4 v[218:219], off
	v_lshl_add_u64 v[208:209], s[40:41], 0, v[186:187]
	s_mov_b32 m0, s77
	v_lshl_add_u64 v[226:227], s[72:73], 0, v[184:185]
	global_load_lds_dwordx4 v[208:209], off
	v_lshl_add_u64 v[208:209], s[40:41], 0, v[190:191]
	s_add_i32 m0, s77, 0x2000
	v_lshl_add_u64 v[228:229], s[72:73], 0, v[188:189]
	global_load_lds_dwordx4 v[208:209], off
	s_mov_b32 m0, s81
	s_nop 0
	global_load_lds_dwordx4 v[226:227], off
	s_mov_b32 m0, s82
	s_nop 0
	global_load_lds_dwordx4 v[228:229], off
	s_waitcnt vmcnt(8)
	s_waitcnt lgkmcnt(0)
	s_barrier
	v_mfma_f32_16x16x32_bf16 v[128:131], v[44:47], v[108:111], v[128:131]
	v_mfma_f32_16x16x32_bf16 v[64:67], v[56:59], v[108:111], v[64:67]
	v_mfma_f32_16x16x32_bf16 v[100:103], v[44:47], v[144:147], v[100:103]
	v_mfma_f32_16x16x32_bf16 v[88:91], v[56:59], v[144:147], v[88:91]
	v_mfma_f32_16x16x32_bf16 v[28:31], v[44:47], v[168:171], v[28:31]
	v_mfma_f32_16x16x32_bf16 v[24:27], v[56:59], v[168:171], v[24:27]
	v_mfma_f32_16x16x32_bf16 v[44:47], v[44:47], v[200:203], v[176:179]
	v_mfma_f32_16x16x32_bf16 v[32:35], v[76:79], v[108:111], v[32:35]
	v_mfma_f32_16x16x32_bf16 v[20:23], v[68:71], v[144:147], v[20:23]
	v_mfma_f32_16x16x32_bf16 v[16:19], v[76:79], v[144:147], v[16:19]
	v_mfma_f32_16x16x32_bf16 v[12:15], v[68:71], v[168:171], v[12:15]
	v_mfma_f32_16x16x32_bf16 v[8:11], v[76:79], v[168:171], v[8:11]
	v_mfma_f32_16x16x32_bf16 v[4:7], v[68:71], v[200:203], v[4:7]
	v_mfma_f32_16x16x32_bf16 v[0:3], v[76:79], v[200:203], v[0:3]
	v_mfma_f32_16x16x32_bf16 v[128:131], v[48:51], v[140:143], v[128:131]
	v_mfma_f32_16x16x32_bf16 v[64:67], v[60:63], v[140:143], v[64:67]
	v_mfma_f32_16x16x32_bf16 v[100:103], v[48:51], v[148:151], v[100:103]
	v_mfma_f32_16x16x32_bf16 v[88:91], v[60:63], v[148:151], v[88:91]
	v_mfma_f32_16x16x32_bf16 v[28:31], v[48:51], v[180:183], v[28:31]
	v_mfma_f32_16x16x32_bf16 v[24:27], v[60:63], v[180:183], v[24:27]
	v_mfma_f32_16x16x32_bf16 v[44:47], v[48:51], v[204:207], v[44:47]
	v_mfma_f32_16x16x32_bf16 v[48:51], v[56:59], v[200:203], v[52:55]
	v_mfma_f32_16x16x32_bf16 v[52:55], v[68:71], v[108:111], v[80:83]
	v_mfma_f32_16x16x32_bf16 v[32:35], v[84:87], v[140:143], v[32:35]
	v_mfma_f32_16x16x32_bf16 v[20:23], v[72:75], v[148:151], v[20:23]
	v_mfma_f32_16x16x32_bf16 v[16:19], v[84:87], v[148:151], v[16:19]
	v_mfma_f32_16x16x32_bf16 v[12:15], v[72:75], v[180:183], v[12:15]
	v_mfma_f32_16x16x32_bf16 v[8:11], v[84:87], v[180:183], v[8:11]
	v_mfma_f32_16x16x32_bf16 v[4:7], v[72:75], v[204:207], v[4:7]
	v_mfma_f32_16x16x32_bf16 v[0:3], v[84:87], v[204:207], v[0:3]
	v_mfma_f32_16x16x32_bf16 v[48:51], v[60:63], v[204:207], v[48:51]
	v_mfma_f32_16x16x32_bf16 v[56:59], v[72:75], v[140:143], v[52:55]
	s_barrier
; #define PG8_STAGE(bufoff, gbase, voff) do { _Pragma("unroll") for (int _i = 0; _i < 2; ++_i) \
;         __builtin_amdgcn_global_load_lds((const unsigned*)((const char*)(gbase) + (voff)[_i]), (PG8_LAS unsigned*)(lds + (bufoff) + ldsw + _i * 8192), 16, 0, 0); } while (0)
; #define PG8_LDA(dst, b, h) do { _Pragma("unroll") for (int m = 0; m < 4; ++m) _Pragma("unroll") for (int k = 0; k < 2; ++k) dst[m][k] = *(const PG8_LAS bf16x8*)(lds + PG8_SA(b, h) + aoff + m * 2048 + k * 1024); } while (0)
; #define PG8_LDB(dst, b, h) do { _Pragma("unroll") for (int n = 0; n < 2; ++n) _Pragma("unroll") for (int k = 0; k < 2; ++k) dst[n][k] = *(const PG8_LAS bf16x8*)(lds + PG8_SB(b, h) + boff + n * 2048 + k * 1024); } while (0)
; #define PG8_MMA(ai, bj, At, Bt) do { _Pragma("unroll") for (int m = 0; m < 4; ++m) _Pragma("unroll") for (int n = 0; n < 2; ++n) _Pragma("unroll") for (int k = 0; k < 2; ++k) \
;         acc[ai][bj][m][n] = __builtin_amdgcn_mfma_f32_16x16x32_bf16(Bt[n][k], At[m][k], acc[ai][bj][m][n], 0, 0, 0); } while (0)
; #define PG8_WAIT_V(n) asm volatile("s_waitcnt vmcnt(" #n ")" ::: "memory")
; #define PG8_WAIT_L(n) asm volatile("s_waitcnt lgkmcnt(" #n ")" ::: "memory")
; #define PG8_BAR __builtin_amdgcn_s_barrier()
; #define PG8_SCHED __builtin_amdgcn_sched_barrier(0)
; template <class Epi, class Sched, bool ALIGN_EPI = false, bool SP2 = false>
; __device__ __forceinline__ void gemm_phase(PG8_LAS unsigned char* lds, const Gemm g, const Sched& S, const Epi& E, const int wave_id_in) {
;     ...
;             PG8_LDB(B0, 1, 0); PG8_LDB(B1, 1, 1); PG8_SCHED; PG8_LDA(At, 1, 0); PG8_STAGE(PG8_SA(0, 1), a2 + hstep, voffA);
;             PG8_WAIT_V(8); PG8_WAIT_L(0); PG8_BAR; __builtin_amdgcn_s_setprio(1); PG8_MMA(0, 0, At, B0); PG8_MMA(0, 1, At, B1); __builtin_amdgcn_s_setprio(0); PG8_BAR; PG8_SCHED;
;             PG8_LDA(At, 1, 1); PG8_STAGE(PG8_SB(1, 0), b3, voffB); PG8_STAGE(PG8_SB(1, 1), b3 + hstep, voffB); PG8_STAGE(PG8_SA(1, 0), a3, voffA);
;             PG8_WAIT_V(8); PG8_WAIT_L(0); PG8_BAR; __builtin_amdgcn_s_setprio(1); PG8_MMA(1, 0, At, B0); PG8_MMA(1, 1, At, B1); __builtin_amdgcn_s_setprio(0); PG8_BAR; PG8_SCHED;
	s_add_i32 s77, 0, 0x18000
	s_add_i32 s76, 0, 0x1c000
	v_add_u32_e32 v72, s77, v220
	v_add_u32_e32 v80, s76, v220
	ds_read_b128 v[52:55], v72
	ds_read_b128 v[60:63], v72 offset:1024
	ds_read_b128 v[68:71], v72 offset:2048
	ds_read_b128 v[72:75], v72 offset:3072
	ds_read_b128 v[76:79], v80
	ds_read_b128 v[84:87], v80 offset:1024
	ds_read_b128 v[168:171], v80 offset:2048
	ds_read_b128 v[180:183], v80 offset:3072
	s_add_u32 s40, s72, 0x80000
	s_addc_u32 s41, s73, 0
	s_mov_b32 m0, s83
	v_lshl_add_u64 v[148:149], s[40:41], 0, v[184:185]
	ds_read_b128 v[80:83], v223 offset:32768
	ds_read_b128 v[108:111], v223 offset:33792
	ds_read_b128 v[140:143], v223 offset:34816
	ds_read_b128 v[144:147], v223 offset:35840
	ds_read_b128 v[176:179], v223 offset:36864
	ds_read_b128 v[200:203], v223 offset:37888
	ds_read_b128 v[204:207], v223 offset:38912
	ds_read_b128 v[208:211], v223 offset:39936
	global_load_lds_dwordx4 v[148:149], off
	v_lshl_add_u64 v[148:149], s[40:41], 0, v[188:189]
	s_mov_b32 m0, s84
	s_nop 0
	global_load_lds_dwordx4 v[148:149], off
	s_waitcnt vmcnt(8)
	s_waitcnt lgkmcnt(0)
	s_barrier
	v_mfma_f32_16x16x32_bf16 v[148:151], v[52:55], v[140:143], v[172:175]
	v_mfma_f32_16x16x32_bf16 v[172:175], v[60:63], v[144:147], v[148:151]
	v_mfma_f32_16x16x32_bf16 v[148:151], v[68:71], v[140:143], v[164:167]
	v_mfma_f32_16x16x32_bf16 v[164:167], v[72:75], v[144:147], v[148:151]
	v_mfma_f32_16x16x32_bf16 v[148:151], v[52:55], v[176:179], v[156:159]
	v_mfma_f32_16x16x32_bf16 v[40:43], v[52:55], v[80:83], v[40:43]
	v_mfma_f32_16x16x32_bf16 v[36:39], v[68:71], v[80:83], v[36:39]
	v_mfma_f32_16x16x32_bf16 v[156:159], v[60:63], v[200:203], v[148:151]
	v_mfma_f32_16x16x32_bf16 v[148:151], v[68:71], v[176:179], v[152:155]
	v_mfma_f32_16x16x32_bf16 v[104:107], v[76:79], v[80:83], v[104:107]
	v_mfma_f32_16x16x32_bf16 v[80:83], v[168:171], v[80:83], v[92:95]
	v_mfma_f32_16x16x32_bf16 v[40:43], v[60:63], v[108:111], v[40:43]
	v_mfma_f32_16x16x32_bf16 v[36:39], v[72:75], v[108:111], v[36:39]
	v_mfma_f32_16x16x32_bf16 v[152:155], v[72:75], v[200:203], v[148:151]
	v_mfma_f32_16x16x32_bf16 v[148:151], v[52:55], v[204:207], v[160:163]
	v_mfma_f32_16x16x32_bf16 v[104:107], v[84:87], v[108:111], v[104:107]
	v_mfma_f32_16x16x32_bf16 v[108:111], v[180:183], v[108:111], v[80:83]
	v_mfma_f32_16x16x32_bf16 v[80:83], v[76:79], v[140:143], v[96:99]
	v_mfma_f32_16x16x32_bf16 v[160:163], v[60:63], v[208:211], v[148:151]
	v_mfma_f32_16x16x32_bf16 v[148:151], v[84:87], v[144:147], v[80:83]
	v_mfma_f32_16x16x32_bf16 v[80:83], v[168:171], v[140:143], v[120:123]
	v_mfma_f32_16x16x32_bf16 v[144:147], v[180:183], v[144:147], v[80:83]
	v_mfma_f32_16x16x32_bf16 v[80:83], v[76:79], v[176:179], v[124:127]
	v_mfma_f32_16x16x32_bf16 v[140:143], v[84:87], v[200:203], v[80:83]
	v_mfma_f32_16x16x32_bf16 v[80:83], v[168:171], v[176:179], v[136:139]
	v_mfma_f32_16x16x32_bf16 v[136:139], v[180:183], v[200:203], v[80:83]
	v_mfma_f32_16x16x32_bf16 v[80:83], v[76:79], v[204:207], v[116:119]
	v_mfma_f32_16x16x32_bf16 v[132:135], v[68:71], v[204:207], v[132:135]
	v_mfma_f32_16x16x32_bf16 v[116:119], v[84:87], v[208:211], v[80:83]
	v_mfma_f32_16x16x32_bf16 v[80:83], v[168:171], v[204:207], v[112:115]
	v_mfma_f32_16x16x32_bf16 v[132:135], v[72:75], v[208:211], v[132:135]
	v_mfma_f32_16x16x32_bf16 v[112:115], v[180:183], v[208:211], v[80:83]
	s_barrier
	s_add_i32 s40, s77, s80
	s_nop 2
	s_nop 0
	v_lshl_add_u64 v[80:81], v[216:217], 0, s[34:35]
	s_mov_b32 m0, s40
	ds_read_b128 v[92:95], v223 offset:49152
	ds_read_b128 v[96:99], v223 offset:50176
	ds_read_b128 v[120:123], v223 offset:51200
	ds_read_b128 v[124:127], v223 offset:52224
	ds_read_b128 v[200:203], v223 offset:53248
	ds_read_b128 v[204:207], v223 offset:54272
	ds_read_b128 v[208:211], v223 offset:55296
	ds_read_b128 v[212:215], v223 offset:56320
	global_load_lds_dwordx4 v[80:81], off
	s_add_i32 m0, s40, 0x2000
	s_add_u32 s12, s12, 0x80080
	v_lshl_add_u64 v[80:81], v[218:219], 0, s[34:35]
	s_addc_u32 s13, s13, 0
	s_add_i32 s40, s76, s80
	global_load_lds_dwordx4 v[80:81], off
	v_lshl_add_u64 v[80:81], s[12:13], 0, v[186:187]
	s_mov_b32 m0, s40
	s_nop 0
	global_load_lds_dwordx4 v[80:81], off
	v_lshl_add_u64 v[80:81], s[12:13], 0, v[190:191]
	s_add_i32 m0, s40, 0x2000
	s_nop 0
	global_load_lds_dwordx4 v[80:81], off
	v_lshl_add_u64 v[80:81], v[226:227], 0, s[34:35]
	s_mov_b32 m0, s87
	s_nop 0
	global_load_lds_dwordx4 v[80:81], off
	v_lshl_add_u64 v[80:81], v[228:229], 0, s[34:35]
	s_mov_b32 m0, s88
	s_nop 0
	global_load_lds_dwordx4 v[80:81], off
	s_waitcnt vmcnt(8)
	s_waitcnt lgkmcnt(0)
	s_barrier
	v_mfma_f32_16x16x32_bf16 v[80:83], v[52:55], v[92:95], v[128:131]
	v_mfma_f32_16x16x32_bf16 v[44:47], v[52:55], v[208:211], v[44:47]
	v_mfma_f32_16x16x32_bf16 v[128:131], v[60:63], v[96:99], v[80:83]
	v_mfma_f32_16x16x32_bf16 v[80:83], v[52:55], v[120:123], v[100:103]
	v_mfma_f32_16x16x32_bf16 v[176:179], v[60:63], v[212:215], v[44:47]
	v_mfma_f32_16x16x32_bf16 v[44:47], v[68:71], v[208:211], v[48:51]
	v_mfma_f32_16x16x32_bf16 v[64:67], v[68:71], v[92:95], v[64:67]
	v_mfma_f32_16x16x32_bf16 v[100:103], v[60:63], v[124:127], v[80:83]
	v_mfma_f32_16x16x32_bf16 v[80:83], v[68:71], v[120:123], v[88:91]
	v_mfma_f32_16x16x32_bf16 v[28:31], v[52:55], v[200:203], v[28:31]
	v_mfma_f32_16x16x32_bf16 v[24:27], v[68:71], v[200:203], v[24:27]
	v_mfma_f32_16x16x32_bf16 v[52:55], v[72:75], v[212:215], v[44:47]
	v_mfma_f32_16x16x32_bf16 v[44:47], v[76:79], v[92:95], v[56:59]
	v_mfma_f32_16x16x32_bf16 v[32:35], v[168:171], v[92:95], v[32:35]
	v_mfma_f32_16x16x32_bf16 v[20:23], v[76:79], v[120:123], v[20:23]
	v_mfma_f32_16x16x32_bf16 v[16:19], v[168:171], v[120:123], v[16:19]
	v_mfma_f32_16x16x32_bf16 v[12:15], v[76:79], v[200:203], v[12:15]
	v_mfma_f32_16x16x32_bf16 v[8:11], v[168:171], v[200:203], v[8:11]
	v_mfma_f32_16x16x32_bf16 v[4:7], v[76:79], v[208:211], v[4:7]
	v_mfma_f32_16x16x32_bf16 v[0:3], v[168:171], v[208:211], v[0:3]
	v_mfma_f32_16x16x32_bf16 v[64:67], v[72:75], v[96:99], v[64:67]
	v_mfma_f32_16x16x32_bf16 v[88:91], v[72:75], v[124:127], v[80:83]
	v_mfma_f32_16x16x32_bf16 v[28:31], v[60:63], v[204:207], v[28:31]
	v_mfma_f32_16x16x32_bf16 v[24:27], v[72:75], v[204:207], v[24:27]
	v_mfma_f32_16x16x32_bf16 v[80:83], v[84:87], v[96:99], v[44:47]
	v_mfma_f32_16x16x32_bf16 v[32:35], v[180:183], v[96:99], v[32:35]
	v_mfma_f32_16x16x32_bf16 v[20:23], v[84:87], v[124:127], v[20:23]
	v_mfma_f32_16x16x32_bf16 v[16:19], v[180:183], v[124:127], v[16:19]
	v_mfma_f32_16x16x32_bf16 v[12:15], v[84:87], v[204:207], v[12:15]
	v_mfma_f32_16x16x32_bf16 v[8:11], v[180:183], v[204:207], v[8:11]
	v_mfma_f32_16x16x32_bf16 v[4:7], v[84:87], v[212:215], v[4:7]
	v_mfma_f32_16x16x32_bf16 v[0:3], v[180:183], v[212:215], v[0:3]
	s_barrier
	s_add_i32 vcc_hi, vcc_hi, 2
	s_add_u32 s10, s10, 0x100
	s_addc_u32 s11, s11, 0
	s_add_u32 s75, s75, 0x100
	s_addc_u32 vcc_lo, vcc_lo, 0
	s_cmp_gt_u32 vcc_hi, 29
	s_cbranch_scc0 .LBB0_819
